# FoX tile loop: row-max tree rewritten as 4 interleaved v_max3 chains (100 -> 32 VALU per tile per wave; hipcc emitted 56 max(x,x) canonicalizations)
# speedup vs baseline: 1.0017x; 1.0017x over previous
.LBB0_466:
	s_nop 9
	v_max3_f32 v173, v84, v85, v86
	v_max3_f32 v174, v68, v69, v70
	v_max3_f32 v172, v52, v53, v54
	v_max3_f32 v170, v36, v37, v38
	v_max3_f32 v173, v173, v87, v88
	v_max3_f32 v174, v174, v71, v72
	v_max3_f32 v172, v172, v55, v56
	v_max3_f32 v170, v170, v39, v40
	v_max3_f32 v173, v173, v89, v90
	v_max3_f32 v174, v174, v73, v74
	v_max3_f32 v172, v172, v57, v58
	v_max3_f32 v170, v170, v41, v42
	v_max3_f32 v173, v173, v91, v92
	v_max3_f32 v174, v174, v75, v76
	v_max3_f32 v172, v172, v59, v60
	v_max3_f32 v170, v170, v43, v44
	v_max3_f32 v173, v173, v93, v94
	v_max3_f32 v174, v174, v77, v78
	v_max3_f32 v172, v172, v61, v62
	v_max3_f32 v170, v170, v45, v46
	v_max3_f32 v173, v173, v95, v96
	v_max3_f32 v174, v174, v79, v80
	v_max3_f32 v172, v172, v63, v64
	v_max3_f32 v170, v170, v47, v48
	v_max3_f32 v173, v173, v97, v98
	v_max3_f32 v174, v174, v81, v82
	v_max3_f32 v172, v172, v65, v66
	v_max3_f32 v170, v170, v49, v50
	v_max_f32_e32 v173, v173, v99
	v_max_f32_e32 v174, v174, v83
	v_max_f32_e32 v172, v172, v67
	v_max_f32_e32 v170, v170, v51
	v_max_f32_e32 v0, v172, v170
	v_max3_f32 v0, v173, v174, v0
	ds_bpermute_b32 v171, v161, v0
	s_waitcnt lgkmcnt(0)
	v_max3_f32 v0, v169, v0, v171
	v_cmp_neq_f32_e32 vcc, v0, v169
	s_cbranch_vccz .LBB0_468
	v_sub_f32_e32 v169, v169, v0
	v_exp_f32_e32 v182, v169
	s_nop 0
	v_pk_mul_f32 v[32:33], v[32:33], v[182:183] op_sel_hi:[1,0]
	v_pk_mul_f32 v[30:31], v[30:31], v[182:183] op_sel_hi:[1,0]
	v_pk_mul_f32 v[28:29], v[28:29], v[182:183] op_sel_hi:[1,0]
	v_pk_mul_f32 v[26:27], v[26:27], v[182:183] op_sel_hi:[1,0]
	v_pk_mul_f32 v[24:25], v[24:25], v[182:183] op_sel_hi:[1,0]
	v_pk_mul_f32 v[22:23], v[22:23], v[182:183] op_sel_hi:[1,0]
	v_pk_mul_f32 v[20:21], v[20:21], v[182:183] op_sel_hi:[1,0]
	v_pk_mul_f32 v[18:19], v[18:19], v[182:183] op_sel_hi:[1,0]
	v_pk_mul_f32 v[16:17], v[16:17], v[182:183] op_sel_hi:[1,0]
	v_pk_mul_f32 v[14:15], v[14:15], v[182:183] op_sel_hi:[1,0]
	v_pk_mul_f32 v[12:13], v[12:13], v[182:183] op_sel_hi:[1,0]
	v_pk_mul_f32 v[10:11], v[10:11], v[182:183] op_sel_hi:[1,0]
	v_pk_mul_f32 v[8:9], v[8:9], v[182:183] op_sel_hi:[1,0]
	v_pk_mul_f32 v[6:7], v[6:7], v[182:183] op_sel_hi:[1,0]
	v_pk_mul_f32 v[4:5], v[4:5], v[182:183] op_sel_hi:[1,0]
	v_pk_mul_f32 v[2:3], v[2:3], v[182:183] op_sel_hi:[1,0]
	v_mul_f32_e32 v34, v34, v182
